# unit header of P2/P4/P8: next-unit index math deferred into the peeled first K-tile behind its LDS read and DMA issue
# speedup vs baseline: 1.0100x; 1.0021x over previous
;     __host__ __device__ bool next(int i, Unit& u) const { if (!b.next(i >> 1, u)) return false; u.sel = i & 1; return true; }
; #define PG8_STAGE(bufoff, gbase, voff) do { _Pragma("unroll") for (int _i = 0; _i < 2; ++_i) \
;         __builtin_amdgcn_global_load_lds((const unsigned*)((const char*)(gbase) + (voff)[_i]), (PG8_LAS unsigned*)(lds + (bufoff) + ldsw + _i * 8192), 16, 0, 0); } while (0)
; #define PG8_LDA(dst, b, h) do { _Pragma("unroll") for (int m = 0; m < 4; ++m) _Pragma("unroll") for (int k = 0; k < 2; ++k) dst[m][k] = *(const PG8_LAS bf16x8*)(lds + PG8_SA(b, h) + aoff + m * 2048 + k * 1024); } while (0)
; #define PG8_WAIT_V(n) asm volatile("s_waitcnt vmcnt(" #n ")" ::: "memory")
; #define PG8_WAIT_L(n) asm volatile("s_waitcnt lgkmcnt(" #n ")" ::: "memory")
; #define PG8_BAR __builtin_amdgcn_s_barrier()
;     __host__ __device__ bool next(int i, Unit& u) const {
;         const long L = (long)i * G + c; if (L >= nwg) return false;
;         int wgid = (int)L; { const int q = nwg / NXCD, r = nwg % NXCD, xcd = wgid % NXCD, off = wgid / NXCD; wgid = (xcd < r ? xcd * (q + 1) : r * (q + 1) + (xcd - r) * q) + off; }
;         const int nig = WGM * nN, gid = wgid / nig, fm = gid * WGM, gsz = (nM - fm) < WGM ? (nM - fm) : WGM;
;         u.pm = fm + ((wgid % nig) % gsz); u.pn = (wgid % nig) / gsz; u.sel = 0; return true;
; template <class Epi, class Sched, bool ALIGN_EPI = false, bool SP2 = false>
; __device__ __forceinline__ void gemm_phase(PG8_LAS unsigned char* lds, const Gemm g, const Sched& S, const Epi& E) {
;     ...
;         const bool has_next = S.next(ui + 1, nxt);
;         const char* nA = has_next ? PG8_ABASE(nxt) : cA; const char* nB = has_next ? PG8_BBASE(nxt) : cB;
;         for (int t = 0; t < nt; t += 2) {
;             const bool last = (t == nt - 2);
;             const char* a1 = cA + (size_t)(t + 1) * kstepA;
;             const char* a2 = last ? nA : cA + (size_t)(t + 2) * kstepA; const char* b2 = last ? nB : cB + (size_t)(t + 2) * kstep;
;             const char* a3 = a2 + kstepA; const char* b3 = b2 + kstep;
;             if (last && has_next) S.a_ready(nxt);
;             if constexpr (SP2) {
;             PG8_LDB(B0, 0, 0); PG8_LDB(B1, 0, 1); PG8_SCHED; PG8_LDA(At, 0, 0); PG8_STAGE(PG8_SA(1, 1), a1 + hstep, voffA);
;             PG8_WAIT_V(8); PG8_WAIT_L(0); PG8_BAR; PG8_MMA(0, 0, At, B0); PG8_MMA(0, 1, At, B1); PG8_BAR; PG8_SCHED;
.LBB0_205:
	s_add_u32 s22, s22, 0x40080
	s_addc_u32 s23, s23, 0
	s_add_u32 s52, s24, 0x100
	s_addc_u32 s53, s25, 0
	s_mov_b32 s54, -2
	ds_read_b128 v[154:157], v150
	ds_read_b128 v[158:161], v150 offset:1024
	ds_read_b128 v[162:165], v150 offset:2048
	ds_read_b128 v[166:169], v150 offset:3072
	ds_read_b128 v[170:173], v151
	ds_read_b128 v[174:177], v151 offset:1024
	ds_read_b128 v[178:181], v151 offset:2048
	ds_read_b128 v[182:185], v151 offset:3072
	s_add_u32 s24, s22, 0xfffc0080
	s_addc_u32 s25, s23, -1
	s_cmp_eq_u32 s54, 12
	s_cselect_b32 s27, s15, s25
	s_cselect_b32 s26, s50, s24
	s_cselect_b32 s25, s13, s53
	s_cselect_b32 s24, s51, s52
	v_lshl_add_u64 v[218:219], s[22:23], 0, v[140:141]
	s_add_i32 m0, s37, 0xc000
	ds_read_b128 v[186:189], v152
	ds_read_b128 v[190:193], v152 offset:1024
	ds_read_b128 v[194:197], v152 offset:2048
	ds_read_b128 v[198:201], v152 offset:3072
	ds_read_b128 v[202:205], v152 offset:4096
	ds_read_b128 v[206:209], v152 offset:5120
	ds_read_b128 v[210:213], v152 offset:6144
	ds_read_b128 v[214:217], v152 offset:7168
	global_load_lds_dwordx4 v[218:219], off
	v_lshl_add_u64 v[218:219], s[22:23], 0, v[142:143]
	s_add_i32 m0, s37, 0xe000
	s_nop 0
	global_load_lds_dwordx4 v[218:219], off
	s_add_i32 s44, s44, 1
	s_mul_i32 s0, s44, s46
	s_mul_hi_u32 s1, s44, s33
	s_add_i32 s1, s1, s0
	s_mul_i32 s0, s44, s33
	s_add_u32 s16, s0, s87
	s_addc_u32 s17, s1, s35
	v_cmp_lt_i64_e64 s[0:1], s[16:17], v[144:145]
	s_ashr_i32 s12, s16, 31
	s_lshr_b32 s12, s12, 29
	s_add_i32 s12, s16, s12
	s_ashr_i32 s13, s12, 3
	s_and_b32 s12, s12, -8
	s_sub_i32 s12, s16, s12
	s_cmp_lt_i32 s12, 0
	s_cselect_b32 s14, s36, 0x160
	s_mul_i32 s12, s12, s14
	s_add_i32 s12, s12, s13
	s_mul_hi_i32 s13, s12, 0x2e8ba2e9
	s_lshr_b32 s14, s13, 31
	s_ashr_i32 s13, s13, 3
	s_add_i32 s13, s13, s14
	s_lshl_b32 s14, s13, 1
	s_mul_i32 s13, s13, 44
	s_sub_i32 s13, s12, s13
	s_lshr_b32 s12, s13, 1
	s_and_b32 s13, s13, 1
	s_add_i32 s14, s14, s13
	s_ashr_i32 s15, s14, 31
	s_lshl_b64 s[16:17], s[14:15], 19
	s_add_u32 s16, s28, s16
	s_addc_u32 s17, s29, s17
	s_and_b64 s[18:19], s[0:1], exec
	s_cselect_b32 s15, s17, s29
	s_cselect_b32 s50, s16, s28
	s_ashr_i32 s13, s12, 31
	s_lshl_b64 s[18:19], s[12:13], 19
	s_add_u32 s18, s30, s18
	s_addc_u32 s19, s31, s19
	s_and_b64 s[98:99], s[0:1], exec
	s_cselect_b32 s13, s19, s31
	s_cselect_b32 s51, s18, s30
	s_waitcnt vmcnt(8)
	s_waitcnt lgkmcnt(0)
	s_barrier
	s_setprio 1
	s_waitcnt lgkmcnt(0)
	v_mfma_f32_16x16x32_bf16 v[126:129], v[154:157], v[186:189], 0
	v_mfma_f32_16x16x32_bf16 v[122:125], v[162:165], v[186:189], 0
	v_mfma_f32_16x16x32_bf16 v[110:113], v[154:157], v[194:197], 0
	v_mfma_f32_16x16x32_bf16 v[106:109], v[162:165], v[194:197], 0
	v_mfma_f32_16x16x32_bf16 v[94:97], v[154:157], v[202:205], 0
	v_mfma_f32_16x16x32_bf16 v[90:93], v[162:165], v[202:205], 0
	v_mfma_f32_16x16x32_bf16 v[78:81], v[154:157], v[210:213], 0
	v_mfma_f32_16x16x32_bf16 v[74:77], v[162:165], v[210:213], 0
	v_mfma_f32_16x16x32_bf16 v[126:129], v[158:161], v[190:193], v[126:129]
	v_mfma_f32_16x16x32_bf16 v[122:125], v[166:169], v[190:193], v[122:125]
	v_mfma_f32_16x16x32_bf16 v[110:113], v[158:161], v[198:201], v[110:113]
	v_mfma_f32_16x16x32_bf16 v[106:109], v[166:169], v[198:201], v[106:109]
	v_mfma_f32_16x16x32_bf16 v[94:97], v[158:161], v[206:209], v[94:97]
	v_mfma_f32_16x16x32_bf16 v[90:93], v[166:169], v[206:209], v[90:93]
	v_mfma_f32_16x16x32_bf16 v[78:81], v[158:161], v[214:217], v[78:81]
	v_mfma_f32_16x16x32_bf16 v[74:77], v[166:169], v[214:217], v[74:77]
	s_setprio 0
	s_setprio 1
	v_mfma_f32_16x16x32_bf16 v[118:121], v[170:173], v[186:189], 0
	v_mfma_f32_16x16x32_bf16 v[114:117], v[178:181], v[186:189], 0
	v_mfma_f32_16x16x32_bf16 v[102:105], v[170:173], v[194:197], 0
	v_mfma_f32_16x16x32_bf16 v[98:101], v[178:181], v[194:197], 0
	v_mfma_f32_16x16x32_bf16 v[86:89], v[170:173], v[202:205], 0
	v_mfma_f32_16x16x32_bf16 v[82:85], v[178:181], v[202:205], 0
	v_mfma_f32_16x16x32_bf16 v[70:73], v[170:173], v[210:213], 0
	v_mfma_f32_16x16x32_bf16 v[66:69], v[178:181], v[210:213], 0
	v_mfma_f32_16x16x32_bf16 v[118:121], v[174:177], v[190:193], v[118:121]
	v_mfma_f32_16x16x32_bf16 v[114:117], v[182:185], v[190:193], v[114:117]
	v_mfma_f32_16x16x32_bf16 v[102:105], v[174:177], v[198:201], v[102:105]
	v_mfma_f32_16x16x32_bf16 v[98:101], v[182:185], v[198:201], v[98:101]
	v_mfma_f32_16x16x32_bf16 v[86:89], v[174:177], v[206:209], v[86:89]
	v_mfma_f32_16x16x32_bf16 v[82:85], v[182:185], v[206:209], v[82:85]
	v_mfma_f32_16x16x32_bf16 v[70:73], v[174:177], v[214:217], v[70:73]
	v_mfma_f32_16x16x32_bf16 v[66:69], v[182:185], v[214:217], v[66:69]
	s_setprio 0
	s_barrier
; #define PG8_STAGE(bufoff, gbase, voff) do { _Pragma("unroll") for (int _i = 0; _i < 2; ++_i) \
;         __builtin_amdgcn_global_load_lds((const unsigned*)((const char*)(gbase) + (voff)[_i]), (PG8_LAS unsigned*)(lds + (bufoff) + ldsw + _i * 8192), 16, 0, 0); } while (0)
; #define PG8_LDA(dst, b, h) do { _Pragma("unroll") for (int m = 0; m < 4; ++m) _Pragma("unroll") for (int k = 0; k < 2; ++k) dst[m][k] = *(const PG8_LAS bf16x8*)(lds + PG8_SA(b, h) + aoff + m * 2048 + k * 1024); } while (0)
; #define PG8_MMA(ai, bj, At, Bt) do { __builtin_amdgcn_s_setprio(1); _Pragma("unroll") for (int m = 0; m < 4; ++m) _Pragma("unroll") for (int n = 0; n < 2; ++n) _Pragma("unroll") for (int k = 0; k < 2; ++k) \
;         acc[ai][bj][m][n] = __builtin_amdgcn_mfma_f32_16x16x32_bf16(Bt[n][k], At[m][k], acc[ai][bj][m][n], 0, 0, 0); __builtin_amdgcn_s_setprio(0); } while (0)
; #define PG8_WAIT_V(n) asm volatile("s_waitcnt vmcnt(" #n ")" ::: "memory")
; #define PG8_WAIT_L(n) asm volatile("s_waitcnt lgkmcnt(" #n ")" ::: "memory")
; #define PG8_BAR __builtin_amdgcn_s_barrier()
; #define PG8_SCHED __builtin_amdgcn_sched_barrier(0)
; template <class Epi, class Sched, bool ALIGN_EPI = false, bool SP2 = false>
; __device__ __forceinline__ void gemm_phase(PG8_LAS unsigned char* lds, const Gemm g, const Sched& S, const Epi& E) {
;     ...
;             PG8_LDA(At, 0, 1); PG8_STAGE(PG8_SB(0, 0), b2, voffB); PG8_STAGE(PG8_SB(0, 1), b2 + hstep, voffB); PG8_STAGE(PG8_SA(0, 0), a2, voffA);
;             PG8_WAIT_V(8); PG8_WAIT_L(0); PG8_BAR; PG8_MMA(1, 0, At, B0); PG8_MMA(1, 1, At, B1); PG8_BAR; PG8_SCHED;
	s_add_i32 s55, s47, s34
	v_lshl_add_u64 v[218:219], s[24:25], 0, v[134:135]
	s_mov_b32 m0, s55
	ds_read_b128 v[186:189], v152 offset:16384
	ds_read_b128 v[190:193], v152 offset:17408
	ds_read_b128 v[194:197], v152 offset:18432
	ds_read_b128 v[198:201], v152 offset:19456
	ds_read_b128 v[202:205], v152 offset:20480
	ds_read_b128 v[206:209], v152 offset:21504
	ds_read_b128 v[210:213], v152 offset:22528
	ds_read_b128 v[214:217], v152 offset:23552
	global_load_lds_dwordx4 v[218:219], off
	s_add_i32 m0, s55, 0x2000
	s_add_u32 s56, s24, 0x40000
	v_lshl_add_u64 v[222:223], s[24:25], 0, v[130:131]
	s_addc_u32 s57, s25, 0
	s_add_i32 s55, s48, s34
	global_load_lds_dwordx4 v[222:223], off
	v_lshl_add_u64 v[224:225], s[56:57], 0, v[134:135]
	s_mov_b32 m0, s55
	v_lshl_add_u64 v[226:227], s[26:27], 0, v[132:133]
	global_load_lds_dwordx4 v[224:225], off
	v_lshl_add_u64 v[224:225], s[56:57], 0, v[130:131]
	s_add_i32 m0, s55, 0x2000
	s_nop 0
	global_load_lds_dwordx4 v[224:225], off
	v_lshl_add_u64 v[224:225], s[26:27], 0, v[136:137]
	s_mov_b32 m0, s37
	s_nop 0
	global_load_lds_dwordx4 v[224:225], off
	s_mov_b32 m0, s38
	s_nop 0
	global_load_lds_dwordx4 v[226:227], off
	s_waitcnt vmcnt(8)
	s_waitcnt lgkmcnt(0)
	s_barrier
	s_setprio 1
	s_waitcnt lgkmcnt(0)
	v_mfma_f32_16x16x32_bf16 v[62:65], v[154:157], v[186:189], 0
	v_mfma_f32_16x16x32_bf16 v[58:61], v[162:165], v[186:189], 0
	v_mfma_f32_16x16x32_bf16 v[46:49], v[154:157], v[194:197], 0
	v_mfma_f32_16x16x32_bf16 v[42:45], v[162:165], v[194:197], 0
	v_mfma_f32_16x16x32_bf16 v[30:33], v[154:157], v[202:205], 0
	v_mfma_f32_16x16x32_bf16 v[26:29], v[162:165], v[202:205], 0
	v_mfma_f32_16x16x32_bf16 v[14:17], v[154:157], v[210:213], 0
	v_mfma_f32_16x16x32_bf16 v[10:13], v[162:165], v[210:213], 0
	v_mfma_f32_16x16x32_bf16 v[62:65], v[158:161], v[190:193], v[62:65]
	v_mfma_f32_16x16x32_bf16 v[58:61], v[166:169], v[190:193], v[58:61]
	v_mfma_f32_16x16x32_bf16 v[46:49], v[158:161], v[198:201], v[46:49]
	v_mfma_f32_16x16x32_bf16 v[42:45], v[166:169], v[198:201], v[42:45]
	v_mfma_f32_16x16x32_bf16 v[30:33], v[158:161], v[206:209], v[30:33]
	v_mfma_f32_16x16x32_bf16 v[26:29], v[166:169], v[206:209], v[26:29]
	v_mfma_f32_16x16x32_bf16 v[14:17], v[158:161], v[214:217], v[14:17]
	v_mfma_f32_16x16x32_bf16 v[10:13], v[166:169], v[214:217], v[10:13]
	s_setprio 0
	s_setprio 1
	v_mfma_f32_16x16x32_bf16 v[54:57], v[170:173], v[186:189], 0
	v_mfma_f32_16x16x32_bf16 v[50:53], v[178:181], v[186:189], 0
	v_mfma_f32_16x16x32_bf16 v[38:41], v[170:173], v[194:197], 0
	v_mfma_f32_16x16x32_bf16 v[34:37], v[178:181], v[194:197], 0
	v_mfma_f32_16x16x32_bf16 v[22:25], v[170:173], v[202:205], 0
	v_mfma_f32_16x16x32_bf16 v[18:21], v[178:181], v[202:205], 0
	v_mfma_f32_16x16x32_bf16 v[6:9], v[170:173], v[210:213], 0
	v_mfma_f32_16x16x32_bf16 v[2:5], v[178:181], v[210:213], 0
	v_mfma_f32_16x16x32_bf16 v[54:57], v[174:177], v[190:193], v[54:57]
	v_mfma_f32_16x16x32_bf16 v[50:53], v[182:185], v[190:193], v[50:53]
	v_mfma_f32_16x16x32_bf16 v[38:41], v[174:177], v[198:201], v[38:41]
	v_mfma_f32_16x16x32_bf16 v[34:37], v[182:185], v[198:201], v[34:37]
	v_mfma_f32_16x16x32_bf16 v[22:25], v[174:177], v[206:209], v[22:25]
	v_mfma_f32_16x16x32_bf16 v[18:21], v[182:185], v[206:209], v[18:21]
	v_mfma_f32_16x16x32_bf16 v[6:9], v[174:177], v[214:217], v[6:9]
	v_mfma_f32_16x16x32_bf16 v[2:5], v[182:185], v[214:217], v[2:5]
	s_setprio 0
	s_barrier
	s_branch .Lpz1_mid

;     __host__ __device__ bool next(int i, Unit& u) const { if (!b.next(i >> 1, u)) return false; u.sel = i & 1; return true; }
; #define PG8_STAGE(bufoff, gbase, voff) do { _Pragma("unroll") for (int _i = 0; _i < 2; ++_i) \
;         __builtin_amdgcn_global_load_lds((const unsigned*)((const char*)(gbase) + (voff)[_i]), (PG8_LAS unsigned*)(lds + (bufoff) + ldsw + _i * 8192), 16, 0, 0); } while (0)
; #define PG8_LDA(dst, b, h) do { _Pragma("unroll") for (int m = 0; m < 4; ++m) _Pragma("unroll") for (int k = 0; k < 2; ++k) dst[m][k] = *(const PG8_LAS bf16x8*)(lds + PG8_SA(b, h) + aoff + m * 2048 + k * 1024); } while (0)
; #define PG8_WAIT_V(n) asm volatile("s_waitcnt vmcnt(" #n ")" ::: "memory")
;     __host__ __device__ bool next(int i, Unit& u) const {
;         const long L = (long)i * G + c; if (L >= nwg) return false;
;         int wgid = (int)L; { const int q = nwg / NXCD, r = nwg % NXCD, xcd = wgid % NXCD, off = wgid / NXCD; wgid = (xcd < r ? xcd * (q + 1) : r * (q + 1) + (xcd - r) * q) + off; }
;         const int nig = WGM * nN, gid = wgid / nig, fm = gid * WGM, gsz = (nM - fm) < WGM ? (nM - fm) : WGM;
;         u.pm = fm + ((wgid % nig) % gsz); u.pn = (wgid % nig) / gsz; u.sel = 0; return true;
; template <class Epi, class Sched, bool ALIGN_EPI = false, bool SP2 = false>
; __device__ __forceinline__ void gemm_phase(PG8_LAS unsigned char* lds, const Gemm g, const Sched& S, const Epi& E) {
;     ...
;         const bool has_next = S.next(ui + 1, nxt);
;         const char* nA = has_next ? PG8_ABASE(nxt) : cA; const char* nB = has_next ? PG8_BBASE(nxt) : cB;
;         for (int t = 0; t < nt; t += 2) {
;             const bool last = (t == nt - 2);
;             const char* a1 = cA + (size_t)(t + 1) * kstepA;
;             const char* a2 = last ? nA : cA + (size_t)(t + 2) * kstepA; const char* b2 = last ? nB : cB + (size_t)(t + 2) * kstep;
;             const char* a3 = a2 + kstepA; const char* b3 = b2 + kstep;
;             if (last && has_next) S.a_ready(nxt);
;             if constexpr (SP2) {
;             PG8_LDB(B0, 0, 0); PG8_LDB(B1, 0, 1); PG8_SCHED; PG8_LDA(At, 0, 0); PG8_STAGE(PG8_SA(1, 1), a1 + hstep, voffA);
;             PG8_WAIT_V(8); PG8_WAIT_L(0); PG8_BAR; PG8_MMA(0, 0, At, B0); PG8_MMA(0, 1, At, B1); PG8_BAR; PG8_SCHED;
;             if constexpr (Epi::PREFETCH) { if (t == tpf) E.prefetch(cur, wid, lane); }
.LBB0_435:
	s_ashr_i32 s5, s4, 31
	s_lshl_b32 s8, s6, 8
	s_lshl_b64 s[28:29], s[4:5], 14
	s_ashr_i32 s5, s4, 5
	s_ashr_i32 s9, s8, 31
	s_add_u32 s52, s14, s28
	s_mul_hi_i32 s54, s5, 0x6800
	s_mulk_i32 s5, 0x6800
	s_addc_u32 s53, s88, s29
	s_add_u32 s5, s77, s5
	s_addc_u32 s55, s78, s54
	s_lshl_b64 s[28:29], s[8:9], 2
	s_add_u32 s54, s5, s28
	s_addc_u32 s55, s55, s29
	s_add_u32 s5, s56, 0x100
	v_lshl_add_u64 v[196:197], s[10:11], 0, v[188:189]
	v_lshl_add_u64 v[198:199], s[10:11], 0, v[190:191]
	s_addc_u32 s9, s57, 0
	s_mov_b32 s28, 0
	s_mov_b64 s[56:57], 0
	ds_read_b128 v[162:165], v208
	ds_read_b128 v[166:169], v208 offset:1024
	ds_read_b128 v[170:173], v208 offset:2048
	ds_read_b128 v[174:177], v208 offset:3072
	ds_read_b128 v[146:149], v209
	ds_read_b128 v[150:153], v209 offset:1024
	ds_read_b128 v[154:157], v209 offset:2048
	ds_read_b128 v[158:161], v209 offset:3072
	v_lshl_add_u64 v[42:43], v[196:197], 0, s[56:57]
	s_add_i32 m0, s69, 0xc000
	ds_read_b128 v[212:215], v210
	ds_read_b128 v[216:219], v210 offset:1024
	ds_read_b128 v[222:225], v210 offset:2048
	ds_read_b128 v[226:229], v210 offset:3072
	ds_read_b128 v[230:233], v210 offset:4096
	ds_read_b128 v[234:237], v210 offset:5120
	ds_read_b128 v[238:241], v210 offset:6144
	ds_read_b128 v[242:245], v210 offset:7168
	global_load_lds_dwordx4 v[42:43], off
	v_lshl_add_u64 v[42:43], v[198:199], 0, s[56:57]
	s_add_i32 m0, s69, 0xe000
	s_nop 0
	global_load_lds_dwordx4 v[42:43], off
	s_add_i32 s15, s15, 1
	s_mul_i32 s2, s15, s86
	s_mul_hi_u32 s3, s15, s33
	s_add_i32 s3, s3, s2
	s_mul_i32 s2, s15, s33
	v_readlane_b32 s98, v254, 12
	s_add_u32 s100, s2, s98
	s_addc_u32 s101, s3, s87
	v_cmp_lt_i64_e64 s[2:3], s[100:101], v[192:193]
	s_ashr_i32 s98, s100, 31
	s_lshr_b32 s98, s98, 29
	s_add_i32 s98, s100, s98
	s_ashr_i32 s7, s98, 3
	s_and_b32 s98, s98, -8
	s_sub_i32 s98, s100, s98
	s_cmp_lt_i32 s98, 0
	s_movk_i32 s100, 0x1a1
	s_cselect_b32 s100, s100, 0x1a0
	s_mul_i32 s98, s98, s100
	s_add_i32 s98, s98, s7
	s_mul_hi_i32 s7, s98, 0x4ec4ec4f
	s_lshr_b32 s100, s7, 31
	s_ashr_i32 s7, s7, 4
	s_add_i32 s7, s7, s100
	s_lshl_b32 s100, s7, 1
	s_mul_i32 s7, s7, 52
	s_sub_i32 s98, s98, s7
	s_lshr_b32 s44, s98, 1
	s_and_b32 s98, s98, 1
	s_add_i32 s46, s100, s98
	s_ashr_i32 s47, s46, 31
	s_lshl_b64 s[100:101], s[46:47], 19
	s_add_u32 s48, s64, s100
	s_addc_u32 s49, s65, s101
	s_and_b64 s[100:101], s[2:3], exec
	s_cselect_b32 s7, s49, s65
	s_cselect_b32 s31, s48, s64
	s_ashr_i32 s45, s44, 31
	s_lshl_b64 s[100:101], s[44:45], 19
	s_add_u32 s50, s66, s100
	s_addc_u32 s51, s67, s101
	s_and_b64 s[100:101], s[2:3], exec
	s_cselect_b32 s45, s51, s67
	s_cselect_b32 s47, s50, s66
	s_waitcnt vmcnt(8)
	s_waitcnt lgkmcnt(0)
	s_barrier
	s_setprio 1
	s_waitcnt lgkmcnt(0)
	v_mfma_f32_16x16x32_bf16 v[42:45], v[162:165], v[212:215], 0
	v_mfma_f32_16x16x32_bf16 v[46:49], v[170:173], v[212:215], 0
	v_mfma_f32_16x16x32_bf16 v[50:53], v[162:165], v[222:225], 0
	v_mfma_f32_16x16x32_bf16 v[54:57], v[170:173], v[222:225], 0
	v_mfma_f32_16x16x32_bf16 v[110:113], v[162:165], v[230:233], 0
	v_mfma_f32_16x16x32_bf16 v[106:109], v[170:173], v[230:233], 0
	v_mfma_f32_16x16x32_bf16 v[94:97], v[162:165], v[238:241], 0
	v_mfma_f32_16x16x32_bf16 v[90:93], v[170:173], v[238:241], 0
	v_mfma_f32_16x16x32_bf16 v[42:45], v[166:169], v[216:219], v[42:45]
	v_mfma_f32_16x16x32_bf16 v[46:49], v[174:177], v[216:219], v[46:49]
	v_mfma_f32_16x16x32_bf16 v[50:53], v[166:169], v[226:229], v[50:53]
	v_mfma_f32_16x16x32_bf16 v[54:57], v[174:177], v[226:229], v[54:57]
	v_mfma_f32_16x16x32_bf16 v[110:113], v[166:169], v[234:237], v[110:113]
	v_mfma_f32_16x16x32_bf16 v[106:109], v[174:177], v[234:237], v[106:109]
	v_mfma_f32_16x16x32_bf16 v[94:97], v[166:169], v[242:245], v[94:97]
	v_mfma_f32_16x16x32_bf16 v[90:93], v[174:177], v[242:245], v[90:93]
	s_setprio 0
	s_setprio 1
	v_mfma_f32_16x16x32_bf16 v[122:125], v[146:149], v[212:215], 0
	v_mfma_f32_16x16x32_bf16 v[134:137], v[150:153], v[216:219], v[122:125]
	v_mfma_f32_16x16x32_bf16 v[122:125], v[154:157], v[212:215], 0
	v_mfma_f32_16x16x32_bf16 v[118:121], v[146:149], v[222:225], 0
	v_mfma_f32_16x16x32_bf16 v[114:117], v[154:157], v[222:225], 0
	v_mfma_f32_16x16x32_bf16 v[102:105], v[146:149], v[230:233], 0
	v_mfma_f32_16x16x32_bf16 v[98:101], v[154:157], v[230:233], 0
	v_mfma_f32_16x16x32_bf16 v[86:89], v[146:149], v[238:241], 0
	v_mfma_f32_16x16x32_bf16 v[82:85], v[154:157], v[238:241], 0
	v_mfma_f32_16x16x32_bf16 v[130:133], v[158:161], v[216:219], v[122:125]
	v_mfma_f32_16x16x32_bf16 v[118:121], v[150:153], v[226:229], v[118:121]
	v_mfma_f32_16x16x32_bf16 v[114:117], v[158:161], v[226:229], v[114:117]
	v_mfma_f32_16x16x32_bf16 v[102:105], v[150:153], v[234:237], v[102:105]
	v_mfma_f32_16x16x32_bf16 v[98:101], v[158:161], v[234:237], v[98:101]
	v_mfma_f32_16x16x32_bf16 v[86:89], v[150:153], v[242:245], v[86:89]
	v_mfma_f32_16x16x32_bf16 v[82:85], v[158:161], v[242:245], v[82:85]
	s_setprio 0
	s_barrier
	s_cmp_lg_u32 s63, s28
	s_cbranch_scc1 .Lpz3_a
	v_mov_b32_e32 v186, v207
	s_add_i32 m0, s62, 0x20000
	v_lshl_add_u64 v[122:123], s[52:53], 0, v[186:187]
	s_mov_b64 s[58:59], 0x400
	global_load_lds_dwordx4 v186, s[52:53]
	v_lshl_add_u64 v[122:123], v[122:123], 0, s[58:59]
	s_add_i32 m0, s62, 0x20400
	s_andn2_b64 vcc, exec, s[40:41]
	global_load_lds_dwordx4 v[122:123], off
	s_cbranch_vccnz .Lpz3_a
	v_lshl_add_u64 v[122:123], s[54:55], 0, v[186:187]
	s_mov_b32 m0, s30
	s_nop 0
	global_load_lds_dwordx4 v[122:123], off
	s_branch .Lpz3_a

;     __host__ __device__ bool next(int i, Unit& u) const { if (!b.next(i >> 1, u)) return false; u.sel = i & 1; return true; }
; #define PG8_STAGE(bufoff, gbase, voff) do { _Pragma("unroll") for (int _i = 0; _i < 2; ++_i) \
;         __builtin_amdgcn_global_load_lds((const unsigned*)((const char*)(gbase) + (voff)[_i]), (PG8_LAS unsigned*)(lds + (bufoff) + ldsw + _i * 8192), 16, 0, 0); } while (0)
; #define PG8_LDA(dst, b, h) do { _Pragma("unroll") for (int m = 0; m < 4; ++m) _Pragma("unroll") for (int k = 0; k < 2; ++k) dst[m][k] = *(const PG8_LAS bf16x8*)(lds + PG8_SA(b, h) + aoff + m * 2048 + k * 1024); } while (0)
; #define PG8_WAIT_V(n) asm volatile("s_waitcnt vmcnt(" #n ")" ::: "memory")
;     __host__ __device__ bool next(int i, Unit& u) const {
;         const long L = (long)i * G + c; if (L >= nwg) return false;
;         int wgid = (int)L; { const int q = nwg / NXCD, r = nwg % NXCD, xcd = wgid % NXCD, off = wgid / NXCD; wgid = (xcd < r ? xcd * (q + 1) : r * (q + 1) + (xcd - r) * q) + off; }
;         const int nig = WGM * nN, gid = wgid / nig, fm = gid * WGM, gsz = (nM - fm) < WGM ? (nM - fm) : WGM;
;         u.pm = fm + ((wgid % nig) % gsz); u.pn = (wgid % nig) / gsz; u.sel = 0; return true;
; template <class Epi, class Sched, bool ALIGN_EPI = false, bool SP2 = false>
; __device__ __forceinline__ void gemm_phase(PG8_LAS unsigned char* lds, const Gemm g, const Sched& S, const Epi& E) {
;     ...
;         const bool has_next = S.next(ui + 1, nxt);
;         const char* nA = has_next ? PG8_ABASE(nxt) : cA; const char* nB = has_next ? PG8_BBASE(nxt) : cB;
;         for (int t = 0; t < nt; t += 2) {
;             const bool last = (t == nt - 2);
;             const char* a1 = cA + (size_t)(t + 1) * kstepA;
;             const char* a2 = last ? nA : cA + (size_t)(t + 2) * kstepA; const char* b2 = last ? nB : cB + (size_t)(t + 2) * kstep;
;             const char* a3 = a2 + kstepA; const char* b3 = b2 + kstep;
;             if (last && has_next) S.a_ready(nxt);
;             if constexpr (SP2) {
;             PG8_LDB(B0, 0, 0); PG8_LDB(B1, 0, 1); PG8_SCHED; PG8_LDA(At, 0, 0); PG8_STAGE(PG8_SA(1, 1), a1 + hstep, voffA);
;             PG8_WAIT_V(8); PG8_WAIT_L(0); PG8_BAR; PG8_MMA(0, 0, At, B0); PG8_MMA(0, 1, At, B1); PG8_BAR; PG8_SCHED;
;             if constexpr (Epi::PREFETCH) { if (t == tpf) E.prefetch(cur, wid, lane); }
.LBB0_982:
	s_ashr_i32 s29, s28, 31
	s_lshl_b32 s34, s34, 8
	s_lshl_b64 s[36:37], s[28:29], 14
	s_ashr_i32 s29, s28, 5
	s_ashr_i32 s35, s34, 31
	s_add_u32 s36, s10, s36
	s_mul_hi_i32 s38, s29, 0x5800
	s_mulk_i32 s29, 0x5800
	s_addc_u32 s37, s69, s37
	s_add_u32 s29, s62, s29
	s_addc_u32 s42, s63, s38
	s_lshl_b64 s[38:39], s[34:35], 2
	s_add_u32 s38, s29, s38
	s_addc_u32 s39, s42, s39
	s_add_u32 s29, s40, 0x100
	v_lshl_add_u64 v[188:189], s[30:31], 0, v[180:181]
	v_lshl_add_u64 v[190:191], s[30:31], 0, v[182:183]
	s_addc_u32 s35, s41, 0
	s_mov_b32 s83, 0
	s_mov_b64 s[40:41], 0
	ds_read_b128 v[154:157], v195
	ds_read_b128 v[158:161], v195 offset:1024
	ds_read_b128 v[162:165], v195 offset:2048
	ds_read_b128 v[166:169], v195 offset:3072
	ds_read_b128 v[138:141], v196
	ds_read_b128 v[142:145], v196 offset:1024
	ds_read_b128 v[146:149], v196 offset:2048
	ds_read_b128 v[150:153], v196 offset:3072
	v_lshl_add_u64 v[98:99], v[188:189], 0, s[40:41]
	s_add_i32 m0, s54, 0xc000
	ds_read_b128 v[200:203], v197
	ds_read_b128 v[204:207], v197 offset:1024
	ds_read_b128 v[208:211], v197 offset:2048
	ds_read_b128 v[212:215], v197 offset:3072
	ds_read_b128 v[216:219], v197 offset:4096
	ds_read_b128 v[220:223], v197 offset:5120
	ds_read_b128 v[224:227], v197 offset:6144
	ds_read_b128 v[228:231], v197 offset:7168
	global_load_lds_dwordx4 v[98:99], off
	v_lshl_add_u64 v[98:99], v[190:191], 0, s[40:41]
	s_add_i32 m0, s54, 0xe000
	s_nop 0
	global_load_lds_dwordx4 v[98:99], off
	s_add_i32 s11, s11, 1
	s_mul_i32 s2, s11, s68
	s_mul_hi_u32 s3, s11, s33
	s_add_i32 s3, s3, s2
	s_mul_i32 s2, s11, s33
	s_add_u32 s24, s2, s87
	s_addc_u32 s25, s3, s52
	v_cmp_lt_i64_e64 s[2:3], s[24:25], v[184:185]
	s_ashr_i32 s20, s24, 31
	s_lshr_b32 s20, s20, 29
	s_add_i32 s20, s24, s20
	s_ashr_i32 s21, s20, 3
	s_and_b32 s20, s20, -8
	s_sub_i32 s20, s24, s20
	s_cmp_lt_i32 s20, 0
	s_cselect_b32 s22, s53, 0x160
	s_mul_i32 s20, s20, s22
	s_add_i32 s20, s20, s21
	s_mul_hi_i32 s21, s20, 0x2e8ba2e9
	s_lshr_b32 s22, s21, 31
	s_ashr_i32 s21, s21, 3
	s_add_i32 s21, s21, s22
	s_lshl_b32 s22, s21, 1
	s_mul_i32 s21, s21, 44
	s_sub_i32 s21, s20, s21
	s_lshr_b32 s20, s21, 1
	s_and_b32 s21, s21, 1
	s_add_i32 s22, s22, s21
	s_ashr_i32 s23, s22, 31
	s_lshl_b64 s[24:25], s[22:23], 19
	s_add_u32 s24, s47, s24
	s_addc_u32 s25, s48, s25
	s_and_b64 s[26:27], s[2:3], exec
	s_cselect_b32 s23, s25, s48
	s_cselect_b32 s81, s24, s47
	s_ashr_i32 s21, s20, 31
	s_lshl_b64 s[26:27], s[20:21], 19
	s_add_u32 s26, s49, s26
	s_addc_u32 s27, s50, s27
	s_and_b64 s[98:99], s[2:3], exec
	s_cselect_b32 s21, s27, s50
	s_cselect_b32 s82, s26, s49
	s_waitcnt vmcnt(8)
	s_waitcnt lgkmcnt(0)
	s_barrier
	s_setprio 1
	s_waitcnt lgkmcnt(0)
	v_mfma_f32_16x16x32_bf16 v[98:101], v[154:157], v[200:203], 0
	v_mfma_f32_16x16x32_bf16 v[106:109], v[162:165], v[200:203], 0
	v_mfma_f32_16x16x32_bf16 v[118:121], v[154:157], v[208:211], 0
	v_mfma_f32_16x16x32_bf16 v[114:117], v[162:165], v[208:211], 0
	v_mfma_f32_16x16x32_bf16 v[94:97], v[154:157], v[216:219], 0
	v_mfma_f32_16x16x32_bf16 v[90:93], v[162:165], v[216:219], 0
	v_mfma_f32_16x16x32_bf16 v[78:81], v[154:157], v[224:227], 0
	v_mfma_f32_16x16x32_bf16 v[74:77], v[162:165], v[224:227], 0
	v_mfma_f32_16x16x32_bf16 v[98:101], v[158:161], v[204:207], v[98:101]
	v_mfma_f32_16x16x32_bf16 v[106:109], v[166:169], v[204:207], v[106:109]
	v_mfma_f32_16x16x32_bf16 v[118:121], v[158:161], v[212:215], v[118:121]
	v_mfma_f32_16x16x32_bf16 v[114:117], v[166:169], v[212:215], v[114:117]
	v_mfma_f32_16x16x32_bf16 v[94:97], v[158:161], v[220:223], v[94:97]
	v_mfma_f32_16x16x32_bf16 v[90:93], v[166:169], v[220:223], v[90:93]
	v_mfma_f32_16x16x32_bf16 v[78:81], v[158:161], v[228:231], v[78:81]
	v_mfma_f32_16x16x32_bf16 v[74:77], v[166:169], v[228:231], v[74:77]
	s_setprio 0
	s_setprio 1
	v_mfma_f32_16x16x32_bf16 v[126:129], v[138:141], v[200:203], 0
	v_mfma_f32_16x16x32_bf16 v[122:125], v[146:149], v[200:203], 0
	v_mfma_f32_16x16x32_bf16 v[110:113], v[138:141], v[208:211], 0
	v_mfma_f32_16x16x32_bf16 v[102:105], v[146:149], v[208:211], 0
	v_mfma_f32_16x16x32_bf16 v[86:89], v[138:141], v[216:219], 0
	v_mfma_f32_16x16x32_bf16 v[82:85], v[146:149], v[216:219], 0
	v_mfma_f32_16x16x32_bf16 v[70:73], v[138:141], v[224:227], 0
	v_mfma_f32_16x16x32_bf16 v[66:69], v[146:149], v[224:227], 0
	v_mfma_f32_16x16x32_bf16 v[126:129], v[142:145], v[204:207], v[126:129]
	v_mfma_f32_16x16x32_bf16 v[122:125], v[150:153], v[204:207], v[122:125]
	v_mfma_f32_16x16x32_bf16 v[110:113], v[142:145], v[212:215], v[110:113]
	v_mfma_f32_16x16x32_bf16 v[102:105], v[150:153], v[212:215], v[102:105]
	v_mfma_f32_16x16x32_bf16 v[86:89], v[142:145], v[220:223], v[86:89]
	v_mfma_f32_16x16x32_bf16 v[82:85], v[150:153], v[220:223], v[82:85]
	v_mfma_f32_16x16x32_bf16 v[70:73], v[142:145], v[228:231], v[70:73]
	v_mfma_f32_16x16x32_bf16 v[66:69], v[150:153], v[228:231], v[66:69]
	s_setprio 0
	s_barrier
	s_cmp_lg_u32 s46, s83
	s_cbranch_scc1 .Lpz5_a
	v_mov_b32_e32 v178, v194
	s_add_i32 m0, s79, 0x20000
	v_lshl_add_u64 v[130:131], s[36:37], 0, v[178:179]
	global_load_lds_dwordx4 v178, s[36:37]
	v_lshl_add_u64 v[130:131], v[130:131], 0, s[18:19]
	s_add_i32 m0, s79, 0x20400
	s_andn2_b64 vcc, exec, s[14:15]
	global_load_lds_dwordx4 v[130:131], off
	s_cbranch_vccnz .Lpz5_a
	v_lshl_add_u64 v[130:131], s[38:39], 0, v[178:179]
	s_add_i32 m0, 0, 0x24000
	s_nop 0
	global_load_lds_dwordx4 v[130:131], off
	s_branch .Lpz5_a
